# S5 pass B inner loop unrolled x4 with name-rotating input tiles (no register rotation moves, counted vmcnt(12) wait)
# baseline (speedup 1.0000x reference)
; #define LAS __attribute__((address_space(3)))
; __device__ __forceinline__ unsigned cvt_pk_bf16(float lo, float hi) { unsigned r; asm volatile("v_cvt_pk_bf16_f32 %0, %1, %2" : "=v"(r) : "v"(lo), "v"(hi)); return r; }
; #define LDS_WAIT() asm volatile("s_waitcnt lgkmcnt(0)" ::: "memory")
; template <bool PASSB>
; __device__ __forceinline__ void s5_phase(LAS unsigned char* lds, const Params& p) {
;     ...
;         const size_t row0 = (size_t)b * SEQ + (size_t)c * S5_LC;
;         const bf16_t* up = U + ((size_t)g * T + row0 + fr) * 16 + (fq & 1) * 8;
;         bf16x8 au_q0 = (fq < 2) ? *(const bf16x8*)up : zero8;
;         bf16x8 au_q1 = (fq < 2) ? *(const bf16x8*)(up + (size_t)1 * 16 * 16) : zero8;
;         bf16x8 au_q2 = (fq < 2) ? *(const bf16x8*)(up + (size_t)2 * 16 * 16) : zero8;
;         constexpr int NST = S5_LC / 16;
;         for (int st = 0; st < NST; ++st) {
;             const size_t r0 = row0 + st * 16;
;             const bf16x8 au = au_q0; au_q0 = au_q1; au_q1 = au_q2;
;             if (st + 3 < NST) au_q2 = (fq < 2) ? *(const bf16x8*)(up + (size_t)(st + 3) * 16 * 16) : zero8;
; #pragma unroll
;             for (int nb = 0; nb < 8; ++nb) {
;                 const f32x4 d = __builtin_amdgcn_mfma_f32_16x16x32_bf16(au, bfm[nb], (f32x4){0.f, 0.f, 0.f, 0.f}, 0, 0, 0);
;                 *(LAS f32x4*)(BuL + (nb * 16 + fr) * 20 + fq * 4) = d;
;             }
;             LDS_WAIT();
;             f32x4 br4[4], bi4[4];
; #pragma unroll
;             for (int q = 0; q < 4; ++q) { br4[q] = *(const LAS f32x4*)(BuL + lane * 20 + q * 4); bi4[q] = *(const LAS f32x4*)(BuL + (64 + lane) * 20 + q * 4); }
; #pragma unroll
;             for (int t = 0; t < 16; ++t) {
;                 const float bur = br4[t >> 2][t & 3], bui = bi4[t >> 2][t & 3];
;                 const float nr = are * hr - aim * hi + bur, ni = are * hi + aim * hr + bui; hr = nr; hi = ni;
;                 if (PASSB) *(LAS unsigned*)(HbL + t * 272 + lane * 4) = cvt_pk_bf16(hr, hi);
.LBB0_1092:
	s_or_b64 exec, exec, s[24:25]
	v_and_b32_e32 v1, 63, v105
	v_lshl_or_b32 v98, v1, 15, v72
	v_mov_b32_e32 v99, v73
	v_lshl_add_u64 v[64:65], v[98:99], 0, v[64:65]
	v_lshl_add_u64 v[64:65], v[64:65], 0, v[66:67]
	v_lshlrev_b32_e32 v2, 5, v93
	v_mov_b32_e32 v3, v0
	v_lshlrev_b64 v[64:65], 5, v[64:65]
	v_lshl_add_u64 v[2:3], v[82:83], 0, v[2:3]
	v_mov_b32_e32 v89, v88
	v_mov_b32_e32 v93, v92
	v_lshl_add_u64 v[98:99], v[84:85], 0, v[64:65]
	s_mov_b32 s23, 0
	v_mov_b64_e32 v[100:101], v[86:87]
	v_or_b32_e32 v145, v97, v101
	v_or_b32_e32 v144, v96, v100
	v_lshlrev_b64 v[144:145], 11, v[144:145]
	s_mov_b64 s[80:81], 0x1000
	v_lshl_add_u64 v[144:145], v[2:3], 0, v[144:145]
	v_lshl_add_u64 v[146:147], v[144:145], 0, s[80:81]
	s_mov_b64 s[82:83], 0x8000
	v_add_u32_e32 v158, 0x2800, v109
	v_add_u32_e32 v159, 0x2c40, v109
	v_add_u32_e32 v160, 0x3080, v109
	v_add_u32_e32 v161, 0x34c0, v109
	s_waitcnt vmcnt(0)
	v_mov_b32_e32 v64, 0
	v_mov_b32_e32 v65, 0
	v_mov_b32_e32 v66, 0
	v_mov_b32_e32 v67, 0
	s_branch .Ls5u_top_0
.Ls5u_top_0:
	s_waitcnt vmcnt(12)
	s_cmp_gt_u32 s23, 28
	s_cselect_b64 s[24:25], -1, 0
	s_nor_b64 s[28:29], s[0:1], s[24:25]
	s_and_saveexec_b64 s[24:25], s[28:29]
	s_cbranch_execz .Ls5u_body_0
	global_load_dwordx4 v[64:67], v[98:99], off nt
.Ls5u_body_0:
	s_or_b64 exec, exec, s[24:25]
	v_mfma_f32_16x16x32_bf16 v[112:115], v[68:71], v[8:11], 0
	v_mfma_f32_16x16x32_bf16 v[116:119], v[68:71], v[4:7], 0
	s_nop 6
	ds_write_b128 v107, v[112:115]
	s_add_i32 s23, s23, 1
	v_mfma_f32_16x16x32_bf16 v[120:123], v[68:71], v[16:19], 0
	v_lshl_add_u64 v[98:99], v[98:99], 0, s[64:65]
	s_cmp_eq_u32 s23, 32
	v_mfma_f32_16x16x32_bf16 v[124:127], v[68:71], v[12:15], 0
	ds_write_b128 v107, v[116:119] offset:1280
	s_nop 3
	ds_write_b128 v107, v[120:123] offset:2560
	s_nop 1
	ds_write_b128 v107, v[124:127] offset:3840
	v_mfma_f32_16x16x32_bf16 v[128:131], v[68:71], v[20:23], 0
	v_mfma_f32_16x16x32_bf16 v[112:115], v[68:71], v[24:27], 0
	v_mfma_f32_16x16x32_bf16 v[116:119], v[68:71], v[28:31], 0
	s_nop 5
	ds_write_b128 v107, v[128:131] offset:5120
	ds_write_b128 v107, v[112:115] offset:6400
	ds_write_b128 v107, v[116:119] offset:7680
	v_mfma_f32_16x16x32_bf16 v[112:115], v[68:71], v[32:35], 0
	v_mfma_f32_16x16x32_bf16 v[154:157], v[68:71], v[52:55], 0
	s_nop 6
	ds_write_b128 v107, v[112:115] offset:8960
	s_waitcnt lgkmcnt(0)
	ds_read_b128 v[112:115], v108
	ds_read_b128 v[116:119], v108 offset:16
	ds_read_b128 v[120:123], v108 offset:32
	ds_read_b128 v[124:127], v108 offset:48
	ds_read_b128 v[128:131], v108 offset:5120
	ds_read_b128 v[132:135], v108 offset:5136
	ds_read_b128 v[136:139], v108 offset:5152
	ds_read_b128 v[140:143], v108 offset:5168
	s_waitcnt lgkmcnt(3)
	v_fmac_f32_e32 v112, v88, v94
	v_fmac_f32_e32 v128, v88, v95
	v_fma_f32 v112, -v92, v95, v112
	v_fmac_f32_e32 v128, v92, v94
	v_cvt_pk_bf16_f32 v1, v112, v128
	v_fmac_f32_e32 v113, v88, v112
	v_fmac_f32_e32 v129, v88, v128
	v_fma_f32 v113, -v92, v128, v113
	v_fmac_f32_e32 v129, v92, v112
	v_cvt_pk_bf16_f32 v152, v113, v129
	ds_write2_b32 v158, v1, v152 offset0:0 offset1:68
	v_fmac_f32_e32 v114, v88, v113
	v_fmac_f32_e32 v130, v88, v129
	v_fma_f32 v114, -v92, v129, v114
	v_fmac_f32_e32 v130, v92, v113
	v_cvt_pk_bf16_f32 v1, v114, v130
	v_fmac_f32_e32 v115, v88, v114
	v_fmac_f32_e32 v131, v88, v130
	v_fma_f32 v115, -v92, v130, v115
	v_fmac_f32_e32 v131, v92, v114
	v_cvt_pk_bf16_f32 v152, v115, v131
	ds_write2_b32 v158, v1, v152 offset0:136 offset1:204
	s_waitcnt lgkmcnt(4)
	v_fmac_f32_e32 v116, v88, v115
	v_fmac_f32_e32 v132, v88, v131
	v_fma_f32 v116, -v92, v131, v116
	v_fmac_f32_e32 v132, v92, v115
	v_cvt_pk_bf16_f32 v1, v116, v132
	v_fmac_f32_e32 v117, v88, v116
	v_fmac_f32_e32 v133, v88, v132
	v_fma_f32 v117, -v92, v132, v117
	v_fmac_f32_e32 v133, v92, v116
	v_cvt_pk_bf16_f32 v152, v117, v133
	ds_write2_b32 v159, v1, v152 offset0:0 offset1:68
	v_fmac_f32_e32 v118, v88, v117
	v_fmac_f32_e32 v134, v88, v133
	v_fma_f32 v118, -v92, v133, v118
	v_fmac_f32_e32 v134, v92, v117
	v_cvt_pk_bf16_f32 v1, v118, v134
	v_fmac_f32_e32 v119, v88, v118
	v_fmac_f32_e32 v135, v88, v134
	v_fma_f32 v119, -v92, v134, v119
	v_fmac_f32_e32 v135, v92, v118
	v_cvt_pk_bf16_f32 v152, v119, v135
	ds_write2_b32 v159, v1, v152 offset0:136 offset1:204
	s_waitcnt lgkmcnt(5)
	v_fmac_f32_e32 v120, v88, v119
	v_fmac_f32_e32 v136, v88, v135
	v_fma_f32 v120, -v92, v135, v120
	v_fmac_f32_e32 v136, v92, v119
	v_cvt_pk_bf16_f32 v1, v120, v136
	v_fmac_f32_e32 v121, v88, v120
	v_fmac_f32_e32 v137, v88, v136
	v_fma_f32 v121, -v92, v136, v121
	v_fmac_f32_e32 v137, v92, v120
	v_cvt_pk_bf16_f32 v152, v121, v137
	ds_write2_b32 v160, v1, v152 offset0:0 offset1:68
	v_fmac_f32_e32 v122, v88, v121
	v_fmac_f32_e32 v138, v88, v137
	v_fma_f32 v122, -v92, v137, v122
	v_fmac_f32_e32 v138, v92, v121
	v_cvt_pk_bf16_f32 v1, v122, v138
	v_fmac_f32_e32 v123, v88, v122
	v_fmac_f32_e32 v139, v88, v138
	v_fma_f32 v123, -v92, v138, v123
	v_fmac_f32_e32 v139, v92, v122
	v_cvt_pk_bf16_f32 v152, v123, v139
	ds_write2_b32 v160, v1, v152 offset0:136 offset1:204
	s_waitcnt lgkmcnt(6)
	v_fmac_f32_e32 v124, v88, v123
	v_fmac_f32_e32 v140, v88, v139
	v_fma_f32 v124, -v92, v139, v124
	v_fmac_f32_e32 v140, v92, v123
	v_cvt_pk_bf16_f32 v1, v124, v140
	v_fmac_f32_e32 v125, v88, v124
	v_fmac_f32_e32 v141, v88, v140
	v_fma_f32 v125, -v92, v140, v125
	v_fmac_f32_e32 v141, v92, v124
	v_cvt_pk_bf16_f32 v152, v125, v141
	ds_write2_b32 v161, v1, v152 offset0:0 offset1:68
	v_fmac_f32_e32 v126, v88, v125
	v_fmac_f32_e32 v142, v88, v141
	v_fma_f32 v126, -v92, v141, v126
	v_fmac_f32_e32 v142, v92, v125
	v_cvt_pk_bf16_f32 v1, v126, v142
	v_fmac_f32_e32 v127, v88, v126
	v_fmac_f32_e32 v143, v88, v142
	v_fma_f32 v127, -v92, v142, v127
	v_fmac_f32_e32 v143, v92, v126
	v_cvt_pk_bf16_f32 v152, v127, v143
	ds_write2_b32 v161, v1, v152 offset0:136 offset1:204
	v_mov_b32_e32 v94, v127
	v_mov_b32_e32 v95, v143
	s_waitcnt lgkmcnt(0)
; #define LAS __attribute__((address_space(3)))
; __device__ __forceinline__ unsigned cvt_pk_bf16(float lo, float hi) { unsigned r; asm volatile("v_cvt_pk_bf16_f32 %0, %1, %2" : "=v"(r) : "v"(lo), "v"(hi)); return r; }
; #define LDS_WAIT() asm volatile("s_waitcnt lgkmcnt(0)" ::: "memory")
; template <bool PASSB>
; __device__ __forceinline__ void s5_phase(LAS unsigned char* lds, const Params& p) {
;     ...
;         for (int st = 0; st < NST; ++st) {
;             const size_t r0 = row0 + st * 16;
;             const bf16x8 au = au_q0; au_q0 = au_q1; au_q1 = au_q2;
;             if (st + 3 < NST) au_q2 = (fq < 2) ? *(const bf16x8*)(up + (size_t)(st + 3) * 16 * 16) : zero8;
; #pragma unroll
;             for (int nb = 0; nb < 8; ++nb) {
;                 const f32x4 d = __builtin_amdgcn_mfma_f32_16x16x32_bf16(au, bfm[nb], (f32x4){0.f, 0.f, 0.f, 0.f}, 0, 0, 0);
;                 *(LAS f32x4*)(BuL + (nb * 16 + fr) * 20 + fq * 4) = d;
;             }
;             LDS_WAIT();
;             f32x4 br4[4], bi4[4];
; #pragma unroll
;             for (int q = 0; q < 4; ++q) { br4[q] = *(const LAS f32x4*)(BuL + lane * 20 + q * 4); bi4[q] = *(const LAS f32x4*)(BuL + (64 + lane) * 20 + q * 4); }
; #pragma unroll
;             for (int t = 0; t < 16; ++t) {
;                 const float bur = br4[t >> 2][t & 3], bui = bi4[t >> 2][t & 3];
;                 const float nr = are * hr - aim * hi + bur, ni = are * hi + aim * hr + bui; hr = nr; hi = ni;
;                 if (PASSB) *(LAS unsigned*)(HbL + t * 272 + lane * 4) = cvt_pk_bf16(hr, hi);
;     ...
;             if (PASSB) {
;                 LDS_WAIT();
;                 f32x4 y = __builtin_amdgcn_mfma_f32_16x16x32_bf16(au, dfm, (f32x4){0.f, 0.f, 0.f, 0.f}, 0, 0, 0);
; #pragma unroll
;                 for (int ks = 0; ks < 4; ++ks) {
;                     const bf16x8 a = *(const LAS bf16x8*)(HbL + fr * 272 + (ks * 32 + fq * 8) * 2);
;                     y = __builtin_amdgcn_mfma_f32_16x16x32_bf16(a, cfm[ks], y, 0, 0, 0);
;                 }
; #pragma unroll
;                 for (int j = 0; j < 4; ++j) {
;                     const float v = y[j];
;                     const float ge = v * sigmoidf_(1.5957691216057308f * (v + 0.044715f * v * v * v));
;                     YG[(r0 + fq * 4 + j) * 1024 + g * 16 + fr] = (bf16_t)(cvt_pk_bf16(ge, ge) & 0xffffu);
;                 }
;             }
;             LDS_WAIT();
	ds_read_b128 v[112:115], v110 offset:10240
	ds_read_b128 v[116:119], v110 offset:10304
	s_waitcnt lgkmcnt(1)
	v_mfma_f32_16x16x32_bf16 v[154:157], v[112:115], v[36:39], v[154:157]
	ds_read_b128 v[112:115], v110 offset:10368
	s_waitcnt lgkmcnt(1)
	v_mfma_f32_16x16x32_bf16 v[154:157], v[116:119], v[40:43], v[154:157]
	ds_read_b128 v[116:119], v110 offset:10432
	s_waitcnt lgkmcnt(1)
	v_mfma_f32_16x16x32_bf16 v[154:157], v[112:115], v[44:47], v[154:157]
	s_waitcnt lgkmcnt(0)
	v_mfma_f32_16x16x32_bf16 v[154:157], v[116:119], v[48:51], v[154:157]
	s_nop 7
	v_mul_f32_e32 v148, 0x3d372713, v154
	v_mul_f32_e32 v149, 0x3d372713, v155
	v_mul_f32_e32 v150, 0x3d372713, v156
	v_mul_f32_e32 v151, 0x3d372713, v157
	v_mul_f32_e32 v148, v154, v148
	v_mul_f32_e32 v149, v155, v149
	v_mul_f32_e32 v150, v156, v150
	v_mul_f32_e32 v151, v157, v151
	v_fma_f32 v148, v154, v148, v154
	v_fma_f32 v149, v155, v149, v155
	v_fma_f32 v150, v156, v150, v156
	v_fma_f32 v151, v157, v151, v157
	v_mul_f32_e32 v148, 0xc0135761, v148
	v_mul_f32_e32 v149, 0xc0135761, v149
	v_mul_f32_e32 v150, 0xc0135761, v150
	v_mul_f32_e32 v151, 0xc0135761, v151
	v_exp_f32_e32 v148, v148
	v_exp_f32_e32 v149, v149
	v_exp_f32_e32 v150, v150
	v_exp_f32_e32 v151, v151
	v_add_f32_e32 v148, 1.0, v148
	v_add_f32_e32 v149, 1.0, v149
	v_add_f32_e32 v150, 1.0, v150
	v_add_f32_e32 v151, 1.0, v151
	v_rcp_f32_e32 v148, v148
	v_rcp_f32_e32 v149, v149
	v_rcp_f32_e32 v150, v150
	v_rcp_f32_e32 v151, v151
	v_mul_f32_e32 v148, v154, v148
	v_mul_f32_e32 v149, v155, v149
	v_mul_f32_e32 v150, v156, v150
	v_mul_f32_e32 v151, v157, v151
	v_cvt_pk_bf16_f32 v148, v148, v149
	v_cvt_pk_bf16_f32 v150, v150, v151
	global_store_short v[144:145], v148, off
	global_store_short_d16_hi v[144:145], v148, off offset:2048
	global_store_short v[146:147], v150, off
	global_store_short_d16_hi v[146:147], v150, off offset:2048
	v_lshl_add_u64 v[144:145], v[144:145], 0, s[82:83]
	v_lshl_add_u64 v[146:147], v[146:147], 0, s[82:83]
	s_waitcnt lgkmcnt(0)
	s_cbranch_scc1 .LBB0_1061
.Ls5u_top_1:
	s_waitcnt vmcnt(12)
	s_cmp_gt_u32 s23, 28
	s_cselect_b64 s[24:25], -1, 0
	s_nor_b64 s[28:29], s[0:1], s[24:25]
	s_and_saveexec_b64 s[24:25], s[28:29]
	s_cbranch_execz .Ls5u_body_1
	global_load_dwordx4 v[68:71], v[98:99], off nt
.Ls5u_body_1:
	s_or_b64 exec, exec, s[24:25]
	v_mfma_f32_16x16x32_bf16 v[112:115], v[56:59], v[8:11], 0
	v_mfma_f32_16x16x32_bf16 v[116:119], v[56:59], v[4:7], 0
	s_nop 6
	ds_write_b128 v107, v[112:115]
	s_add_i32 s23, s23, 1
	v_mfma_f32_16x16x32_bf16 v[120:123], v[56:59], v[16:19], 0
	v_lshl_add_u64 v[98:99], v[98:99], 0, s[64:65]
	s_cmp_eq_u32 s23, 32
	v_mfma_f32_16x16x32_bf16 v[124:127], v[56:59], v[12:15], 0
	ds_write_b128 v107, v[116:119] offset:1280
	s_nop 3
	ds_write_b128 v107, v[120:123] offset:2560
	s_nop 1
	ds_write_b128 v107, v[124:127] offset:3840
	v_mfma_f32_16x16x32_bf16 v[128:131], v[56:59], v[20:23], 0
	v_mfma_f32_16x16x32_bf16 v[112:115], v[56:59], v[24:27], 0
	v_mfma_f32_16x16x32_bf16 v[116:119], v[56:59], v[28:31], 0
	s_nop 5
	ds_write_b128 v107, v[128:131] offset:5120
	ds_write_b128 v107, v[112:115] offset:6400
	ds_write_b128 v107, v[116:119] offset:7680
	v_mfma_f32_16x16x32_bf16 v[112:115], v[56:59], v[32:35], 0
	v_mfma_f32_16x16x32_bf16 v[154:157], v[56:59], v[52:55], 0
	s_nop 6
	ds_write_b128 v107, v[112:115] offset:8960
	s_waitcnt lgkmcnt(0)
	ds_read_b128 v[112:115], v108
	ds_read_b128 v[116:119], v108 offset:16
	ds_read_b128 v[120:123], v108 offset:32
	ds_read_b128 v[124:127], v108 offset:48
	ds_read_b128 v[128:131], v108 offset:5120
	ds_read_b128 v[132:135], v108 offset:5136
	ds_read_b128 v[136:139], v108 offset:5152
	ds_read_b128 v[140:143], v108 offset:5168
	s_waitcnt lgkmcnt(3)
	v_fmac_f32_e32 v112, v88, v94
	v_fmac_f32_e32 v128, v88, v95
	v_fma_f32 v112, -v92, v95, v112
	v_fmac_f32_e32 v128, v92, v94
	v_cvt_pk_bf16_f32 v1, v112, v128
	v_fmac_f32_e32 v113, v88, v112
	v_fmac_f32_e32 v129, v88, v128
	v_fma_f32 v113, -v92, v128, v113
	v_fmac_f32_e32 v129, v92, v112
	v_cvt_pk_bf16_f32 v152, v113, v129
	ds_write2_b32 v158, v1, v152 offset0:0 offset1:68
	v_fmac_f32_e32 v114, v88, v113
	v_fmac_f32_e32 v130, v88, v129
	v_fma_f32 v114, -v92, v129, v114
	v_fmac_f32_e32 v130, v92, v113
	v_cvt_pk_bf16_f32 v1, v114, v130
	v_fmac_f32_e32 v115, v88, v114
	v_fmac_f32_e32 v131, v88, v130
	v_fma_f32 v115, -v92, v130, v115
	v_fmac_f32_e32 v131, v92, v114
	v_cvt_pk_bf16_f32 v152, v115, v131
	ds_write2_b32 v158, v1, v152 offset0:136 offset1:204
	s_waitcnt lgkmcnt(4)
	v_fmac_f32_e32 v116, v88, v115
	v_fmac_f32_e32 v132, v88, v131
	v_fma_f32 v116, -v92, v131, v116
	v_fmac_f32_e32 v132, v92, v115
	v_cvt_pk_bf16_f32 v1, v116, v132
	v_fmac_f32_e32 v117, v88, v116
	v_fmac_f32_e32 v133, v88, v132
	v_fma_f32 v117, -v92, v132, v117
	v_fmac_f32_e32 v133, v92, v116
	v_cvt_pk_bf16_f32 v152, v117, v133
	ds_write2_b32 v159, v1, v152 offset0:0 offset1:68
	v_fmac_f32_e32 v118, v88, v117
	v_fmac_f32_e32 v134, v88, v133
	v_fma_f32 v118, -v92, v133, v118
	v_fmac_f32_e32 v134, v92, v117
	v_cvt_pk_bf16_f32 v1, v118, v134
	v_fmac_f32_e32 v119, v88, v118
	v_fmac_f32_e32 v135, v88, v134
	v_fma_f32 v119, -v92, v134, v119
	v_fmac_f32_e32 v135, v92, v118
	v_cvt_pk_bf16_f32 v152, v119, v135
	ds_write2_b32 v159, v1, v152 offset0:136 offset1:204
	s_waitcnt lgkmcnt(5)
; #define LAS __attribute__((address_space(3)))
; __device__ __forceinline__ unsigned cvt_pk_bf16(float lo, float hi) { unsigned r; asm volatile("v_cvt_pk_bf16_f32 %0, %1, %2" : "=v"(r) : "v"(lo), "v"(hi)); return r; }
; template <bool PASSB>
; __device__ __forceinline__ void s5_phase(LAS unsigned char* lds, const Params& p) {
;     ...
;         for (int st = 0; st < NST; ++st) {
;             const size_t r0 = row0 + st * 16;
;             const bf16x8 au = au_q0; au_q0 = au_q1; au_q1 = au_q2;
;             if (st + 3 < NST) au_q2 = (fq < 2) ? *(const bf16x8*)(up + (size_t)(st + 3) * 16 * 16) : zero8;
; #pragma unroll
;             for (int nb = 0; nb < 8; ++nb) {
;                 const f32x4 d = __builtin_amdgcn_mfma_f32_16x16x32_bf16(au, bfm[nb], (f32x4){0.f, 0.f, 0.f, 0.f}, 0, 0, 0);
;                 *(LAS f32x4*)(BuL + (nb * 16 + fr) * 20 + fq * 4) = d;
;             }
;             LDS_WAIT();
;             f32x4 br4[4], bi4[4];
; #pragma unroll
;             for (int q = 0; q < 4; ++q) { br4[q] = *(const LAS f32x4*)(BuL + lane * 20 + q * 4); bi4[q] = *(const LAS f32x4*)(BuL + (64 + lane) * 20 + q * 4); }
; #pragma unroll
;             for (int t = 0; t < 16; ++t) {
;                 const float bur = br4[t >> 2][t & 3], bui = bi4[t >> 2][t & 3];
;                 const float nr = are * hr - aim * hi + bur, ni = are * hi + aim * hr + bui; hr = nr; hi = ni;
;                 if (PASSB) *(LAS unsigned*)(HbL + t * 272 + lane * 4) = cvt_pk_bf16(hr, hi);
;             }
;             if (PASSB) {
;                 LDS_WAIT();
;                 f32x4 y = __builtin_amdgcn_mfma_f32_16x16x32_bf16(au, dfm, (f32x4){0.f, 0.f, 0.f, 0.f}, 0, 0, 0);
; #pragma unroll
;                 for (int ks = 0; ks < 4; ++ks) {
;                     const bf16x8 a = *(const LAS bf16x8*)(HbL + fr * 272 + (ks * 32 + fq * 8) * 2);
;                     y = __builtin_amdgcn_mfma_f32_16x16x32_bf16(a, cfm[ks], y, 0, 0, 0);
;                 }
; #pragma unroll
;                 for (int j = 0; j < 4; ++j) {
;                     const float v = y[j];
;                     const float ge = v * sigmoidf_(1.5957691216057308f * (v + 0.044715f * v * v * v));
;                     YG[(r0 + fq * 4 + j) * 1024 + g * 16 + fr] = (bf16_t)(cvt_pk_bf16(ge, ge) & 0xffffu);
;                 }
;             }
;             LDS_WAIT();
;         }
	v_fmac_f32_e32 v120, v88, v119
	v_fmac_f32_e32 v136, v88, v135
	v_fma_f32 v120, -v92, v135, v120
	v_fmac_f32_e32 v136, v92, v119
	v_cvt_pk_bf16_f32 v1, v120, v136
	v_fmac_f32_e32 v121, v88, v120
	v_fmac_f32_e32 v137, v88, v136
	v_fma_f32 v121, -v92, v136, v121
	v_fmac_f32_e32 v137, v92, v120
	v_cvt_pk_bf16_f32 v152, v121, v137
	ds_write2_b32 v160, v1, v152 offset0:0 offset1:68
	v_fmac_f32_e32 v122, v88, v121
	v_fmac_f32_e32 v138, v88, v137
	v_fma_f32 v122, -v92, v137, v122
	v_fmac_f32_e32 v138, v92, v121
	v_cvt_pk_bf16_f32 v1, v122, v138
	v_fmac_f32_e32 v123, v88, v122
	v_fmac_f32_e32 v139, v88, v138
	v_fma_f32 v123, -v92, v138, v123
	v_fmac_f32_e32 v139, v92, v122
	v_cvt_pk_bf16_f32 v152, v123, v139
	ds_write2_b32 v160, v1, v152 offset0:136 offset1:204
	s_waitcnt lgkmcnt(6)
	v_fmac_f32_e32 v124, v88, v123
	v_fmac_f32_e32 v140, v88, v139
	v_fma_f32 v124, -v92, v139, v124
	v_fmac_f32_e32 v140, v92, v123
	v_cvt_pk_bf16_f32 v1, v124, v140
	v_fmac_f32_e32 v125, v88, v124
	v_fmac_f32_e32 v141, v88, v140
	v_fma_f32 v125, -v92, v140, v125
	v_fmac_f32_e32 v141, v92, v124
	v_cvt_pk_bf16_f32 v152, v125, v141
	ds_write2_b32 v161, v1, v152 offset0:0 offset1:68
	v_fmac_f32_e32 v126, v88, v125
	v_fmac_f32_e32 v142, v88, v141
	v_fma_f32 v126, -v92, v141, v126
	v_fmac_f32_e32 v142, v92, v125
	v_cvt_pk_bf16_f32 v1, v126, v142
	v_fmac_f32_e32 v127, v88, v126
	v_fmac_f32_e32 v143, v88, v142
	v_fma_f32 v127, -v92, v142, v127
	v_fmac_f32_e32 v143, v92, v126
	v_cvt_pk_bf16_f32 v152, v127, v143
	ds_write2_b32 v161, v1, v152 offset0:136 offset1:204
	v_mov_b32_e32 v94, v127
	v_mov_b32_e32 v95, v143
	s_waitcnt lgkmcnt(0)
	ds_read_b128 v[112:115], v110 offset:10240
	ds_read_b128 v[116:119], v110 offset:10304
	s_waitcnt lgkmcnt(1)
	v_mfma_f32_16x16x32_bf16 v[154:157], v[112:115], v[36:39], v[154:157]
	ds_read_b128 v[112:115], v110 offset:10368
	s_waitcnt lgkmcnt(1)
	v_mfma_f32_16x16x32_bf16 v[154:157], v[116:119], v[40:43], v[154:157]
	ds_read_b128 v[116:119], v110 offset:10432
	s_waitcnt lgkmcnt(1)
	v_mfma_f32_16x16x32_bf16 v[154:157], v[112:115], v[44:47], v[154:157]
	s_waitcnt lgkmcnt(0)
	v_mfma_f32_16x16x32_bf16 v[154:157], v[116:119], v[48:51], v[154:157]
	s_nop 7
	v_mul_f32_e32 v148, 0x3d372713, v154
	v_mul_f32_e32 v149, 0x3d372713, v155
	v_mul_f32_e32 v150, 0x3d372713, v156
	v_mul_f32_e32 v151, 0x3d372713, v157
	v_mul_f32_e32 v148, v154, v148
	v_mul_f32_e32 v149, v155, v149
	v_mul_f32_e32 v150, v156, v150
	v_mul_f32_e32 v151, v157, v151
	v_fma_f32 v148, v154, v148, v154
	v_fma_f32 v149, v155, v149, v155
	v_fma_f32 v150, v156, v150, v156
	v_fma_f32 v151, v157, v151, v157
	v_mul_f32_e32 v148, 0xc0135761, v148
	v_mul_f32_e32 v149, 0xc0135761, v149
	v_mul_f32_e32 v150, 0xc0135761, v150
	v_mul_f32_e32 v151, 0xc0135761, v151
	v_exp_f32_e32 v148, v148
	v_exp_f32_e32 v149, v149
	v_exp_f32_e32 v150, v150
	v_exp_f32_e32 v151, v151
	v_add_f32_e32 v148, 1.0, v148
	v_add_f32_e32 v149, 1.0, v149
	v_add_f32_e32 v150, 1.0, v150
	v_add_f32_e32 v151, 1.0, v151
	v_rcp_f32_e32 v148, v148
	v_rcp_f32_e32 v149, v149
	v_rcp_f32_e32 v150, v150
	v_rcp_f32_e32 v151, v151
	v_mul_f32_e32 v148, v154, v148
	v_mul_f32_e32 v149, v155, v149
	v_mul_f32_e32 v150, v156, v150
	v_mul_f32_e32 v151, v157, v151
	v_cvt_pk_bf16_f32 v148, v148, v149
	v_cvt_pk_bf16_f32 v150, v150, v151
	global_store_short v[144:145], v148, off
	global_store_short_d16_hi v[144:145], v148, off offset:2048
	global_store_short v[146:147], v150, off
	global_store_short_d16_hi v[146:147], v150, off offset:2048
	v_lshl_add_u64 v[144:145], v[144:145], 0, s[82:83]
	v_lshl_add_u64 v[146:147], v[146:147], 0, s[82:83]
	s_waitcnt lgkmcnt(0)
	s_cbranch_scc1 .LBB0_1061
.Ls5u_top_2:
	s_waitcnt vmcnt(12)
	s_cmp_gt_u32 s23, 28
	s_cselect_b64 s[24:25], -1, 0
	s_nor_b64 s[28:29], s[0:1], s[24:25]
	s_and_saveexec_b64 s[24:25], s[28:29]
	s_cbranch_execz .Ls5u_body_2
	global_load_dwordx4 v[56:59], v[98:99], off nt
.Ls5u_body_2:
	s_or_b64 exec, exec, s[24:25]
	v_mfma_f32_16x16x32_bf16 v[112:115], v[60:63], v[8:11], 0
	v_mfma_f32_16x16x32_bf16 v[116:119], v[60:63], v[4:7], 0
	s_nop 6
	ds_write_b128 v107, v[112:115]
	s_add_i32 s23, s23, 1
	v_mfma_f32_16x16x32_bf16 v[120:123], v[60:63], v[16:19], 0
	v_lshl_add_u64 v[98:99], v[98:99], 0, s[64:65]
	s_cmp_eq_u32 s23, 32
	v_mfma_f32_16x16x32_bf16 v[124:127], v[60:63], v[12:15], 0
	ds_write_b128 v107, v[116:119] offset:1280
	s_nop 3
	ds_write_b128 v107, v[120:123] offset:2560
	s_nop 1
	ds_write_b128 v107, v[124:127] offset:3840
	v_mfma_f32_16x16x32_bf16 v[128:131], v[60:63], v[20:23], 0
	v_mfma_f32_16x16x32_bf16 v[112:115], v[60:63], v[24:27], 0
	v_mfma_f32_16x16x32_bf16 v[116:119], v[60:63], v[28:31], 0
	s_nop 5
	ds_write_b128 v107, v[128:131] offset:5120
	ds_write_b128 v107, v[112:115] offset:6400
	ds_write_b128 v107, v[116:119] offset:7680
	v_mfma_f32_16x16x32_bf16 v[112:115], v[60:63], v[32:35], 0
	v_mfma_f32_16x16x32_bf16 v[154:157], v[60:63], v[52:55], 0
	s_nop 6
	ds_write_b128 v107, v[112:115] offset:8960
	s_waitcnt lgkmcnt(0)
	ds_read_b128 v[112:115], v108
	ds_read_b128 v[116:119], v108 offset:16
	ds_read_b128 v[120:123], v108 offset:32
	ds_read_b128 v[124:127], v108 offset:48
	ds_read_b128 v[128:131], v108 offset:5120
	ds_read_b128 v[132:135], v108 offset:5136
	ds_read_b128 v[136:139], v108 offset:5152
	ds_read_b128 v[140:143], v108 offset:5168
	s_waitcnt lgkmcnt(3)
; #define LAS __attribute__((address_space(3)))
; __device__ __forceinline__ unsigned cvt_pk_bf16(float lo, float hi) { unsigned r; asm volatile("v_cvt_pk_bf16_f32 %0, %1, %2" : "=v"(r) : "v"(lo), "v"(hi)); return r; }
; template <bool PASSB>
; __device__ __forceinline__ void s5_phase(LAS unsigned char* lds, const Params& p) {
;     ...
;         for (int st = 0; st < NST; ++st) {
;             const size_t r0 = row0 + st * 16;
;             const bf16x8 au = au_q0; au_q0 = au_q1; au_q1 = au_q2;
;             if (st + 3 < NST) au_q2 = (fq < 2) ? *(const bf16x8*)(up + (size_t)(st + 3) * 16 * 16) : zero8;
; #pragma unroll
;             for (int nb = 0; nb < 8; ++nb) {
;                 const f32x4 d = __builtin_amdgcn_mfma_f32_16x16x32_bf16(au, bfm[nb], (f32x4){0.f, 0.f, 0.f, 0.f}, 0, 0, 0);
;                 *(LAS f32x4*)(BuL + (nb * 16 + fr) * 20 + fq * 4) = d;
;             }
;             LDS_WAIT();
;             f32x4 br4[4], bi4[4];
; #pragma unroll
;             for (int q = 0; q < 4; ++q) { br4[q] = *(const LAS f32x4*)(BuL + lane * 20 + q * 4); bi4[q] = *(const LAS f32x4*)(BuL + (64 + lane) * 20 + q * 4); }
; #pragma unroll
;             for (int t = 0; t < 16; ++t) {
;                 const float bur = br4[t >> 2][t & 3], bui = bi4[t >> 2][t & 3];
;                 const float nr = are * hr - aim * hi + bur, ni = are * hi + aim * hr + bui; hr = nr; hi = ni;
;                 if (PASSB) *(LAS unsigned*)(HbL + t * 272 + lane * 4) = cvt_pk_bf16(hr, hi);
;             }
;             if (PASSB) {
;                 LDS_WAIT();
;                 f32x4 y = __builtin_amdgcn_mfma_f32_16x16x32_bf16(au, dfm, (f32x4){0.f, 0.f, 0.f, 0.f}, 0, 0, 0);
; #pragma unroll
;                 for (int ks = 0; ks < 4; ++ks) {
;                     const bf16x8 a = *(const LAS bf16x8*)(HbL + fr * 272 + (ks * 32 + fq * 8) * 2);
;                     y = __builtin_amdgcn_mfma_f32_16x16x32_bf16(a, cfm[ks], y, 0, 0, 0);
;                 }
; #pragma unroll
;                 for (int j = 0; j < 4; ++j) {
;                     const float v = y[j];
;                     const float ge = v * sigmoidf_(1.5957691216057308f * (v + 0.044715f * v * v * v));
;                     YG[(r0 + fq * 4 + j) * 1024 + g * 16 + fr] = (bf16_t)(cvt_pk_bf16(ge, ge) & 0xffffu);
;                 }
;             }
;             LDS_WAIT();
;         }
	v_fmac_f32_e32 v112, v88, v94
	v_fmac_f32_e32 v128, v88, v95
	v_fma_f32 v112, -v92, v95, v112
	v_fmac_f32_e32 v128, v92, v94
	v_cvt_pk_bf16_f32 v1, v112, v128
	v_fmac_f32_e32 v113, v88, v112
	v_fmac_f32_e32 v129, v88, v128
	v_fma_f32 v113, -v92, v128, v113
	v_fmac_f32_e32 v129, v92, v112
	v_cvt_pk_bf16_f32 v152, v113, v129
	ds_write2_b32 v158, v1, v152 offset0:0 offset1:68
	v_fmac_f32_e32 v114, v88, v113
	v_fmac_f32_e32 v130, v88, v129
	v_fma_f32 v114, -v92, v129, v114
	v_fmac_f32_e32 v130, v92, v113
	v_cvt_pk_bf16_f32 v1, v114, v130
	v_fmac_f32_e32 v115, v88, v114
	v_fmac_f32_e32 v131, v88, v130
	v_fma_f32 v115, -v92, v130, v115
	v_fmac_f32_e32 v131, v92, v114
	v_cvt_pk_bf16_f32 v152, v115, v131
	ds_write2_b32 v158, v1, v152 offset0:136 offset1:204
	s_waitcnt lgkmcnt(4)
	v_fmac_f32_e32 v116, v88, v115
	v_fmac_f32_e32 v132, v88, v131
	v_fma_f32 v116, -v92, v131, v116
	v_fmac_f32_e32 v132, v92, v115
	v_cvt_pk_bf16_f32 v1, v116, v132
	v_fmac_f32_e32 v117, v88, v116
	v_fmac_f32_e32 v133, v88, v132
	v_fma_f32 v117, -v92, v132, v117
	v_fmac_f32_e32 v133, v92, v116
	v_cvt_pk_bf16_f32 v152, v117, v133
	ds_write2_b32 v159, v1, v152 offset0:0 offset1:68
	v_fmac_f32_e32 v118, v88, v117
	v_fmac_f32_e32 v134, v88, v133
	v_fma_f32 v118, -v92, v133, v118
	v_fmac_f32_e32 v134, v92, v117
	v_cvt_pk_bf16_f32 v1, v118, v134
	v_fmac_f32_e32 v119, v88, v118
	v_fmac_f32_e32 v135, v88, v134
	v_fma_f32 v119, -v92, v134, v119
	v_fmac_f32_e32 v135, v92, v118
	v_cvt_pk_bf16_f32 v152, v119, v135
	ds_write2_b32 v159, v1, v152 offset0:136 offset1:204
	s_waitcnt lgkmcnt(5)
	v_fmac_f32_e32 v120, v88, v119
	v_fmac_f32_e32 v136, v88, v135
	v_fma_f32 v120, -v92, v135, v120
	v_fmac_f32_e32 v136, v92, v119
	v_cvt_pk_bf16_f32 v1, v120, v136
	v_fmac_f32_e32 v121, v88, v120
	v_fmac_f32_e32 v137, v88, v136
	v_fma_f32 v121, -v92, v136, v121
	v_fmac_f32_e32 v137, v92, v120
	v_cvt_pk_bf16_f32 v152, v121, v137
	ds_write2_b32 v160, v1, v152 offset0:0 offset1:68
	v_fmac_f32_e32 v122, v88, v121
	v_fmac_f32_e32 v138, v88, v137
	v_fma_f32 v122, -v92, v137, v122
	v_fmac_f32_e32 v138, v92, v121
	v_cvt_pk_bf16_f32 v1, v122, v138
	v_fmac_f32_e32 v123, v88, v122
	v_fmac_f32_e32 v139, v88, v138
	v_fma_f32 v123, -v92, v138, v123
	v_fmac_f32_e32 v139, v92, v122
	v_cvt_pk_bf16_f32 v152, v123, v139
	ds_write2_b32 v160, v1, v152 offset0:136 offset1:204
	s_waitcnt lgkmcnt(6)
	v_fmac_f32_e32 v124, v88, v123
	v_fmac_f32_e32 v140, v88, v139
	v_fma_f32 v124, -v92, v139, v124
	v_fmac_f32_e32 v140, v92, v123
	v_cvt_pk_bf16_f32 v1, v124, v140
	v_fmac_f32_e32 v125, v88, v124
	v_fmac_f32_e32 v141, v88, v140
	v_fma_f32 v125, -v92, v140, v125
	v_fmac_f32_e32 v141, v92, v124
	v_cvt_pk_bf16_f32 v152, v125, v141
	ds_write2_b32 v161, v1, v152 offset0:0 offset1:68
	v_fmac_f32_e32 v126, v88, v125
	v_fmac_f32_e32 v142, v88, v141
	v_fma_f32 v126, -v92, v141, v126
	v_fmac_f32_e32 v142, v92, v125
	v_cvt_pk_bf16_f32 v1, v126, v142
	v_fmac_f32_e32 v127, v88, v126
	v_fmac_f32_e32 v143, v88, v142
	v_fma_f32 v127, -v92, v142, v127
	v_fmac_f32_e32 v143, v92, v126
	v_cvt_pk_bf16_f32 v152, v127, v143
	ds_write2_b32 v161, v1, v152 offset0:136 offset1:204
	v_mov_b32_e32 v94, v127
	v_mov_b32_e32 v95, v143
	s_waitcnt lgkmcnt(0)
	ds_read_b128 v[112:115], v110 offset:10240
	ds_read_b128 v[116:119], v110 offset:10304
	s_waitcnt lgkmcnt(1)
	v_mfma_f32_16x16x32_bf16 v[154:157], v[112:115], v[36:39], v[154:157]
	ds_read_b128 v[112:115], v110 offset:10368
	s_waitcnt lgkmcnt(1)
	v_mfma_f32_16x16x32_bf16 v[154:157], v[116:119], v[40:43], v[154:157]
	ds_read_b128 v[116:119], v110 offset:10432
	s_waitcnt lgkmcnt(1)
	v_mfma_f32_16x16x32_bf16 v[154:157], v[112:115], v[44:47], v[154:157]
	s_waitcnt lgkmcnt(0)
	v_mfma_f32_16x16x32_bf16 v[154:157], v[116:119], v[48:51], v[154:157]
	s_nop 7
	v_mul_f32_e32 v148, 0x3d372713, v154
	v_mul_f32_e32 v149, 0x3d372713, v155
	v_mul_f32_e32 v150, 0x3d372713, v156
	v_mul_f32_e32 v151, 0x3d372713, v157
	v_mul_f32_e32 v148, v154, v148
	v_mul_f32_e32 v149, v155, v149
	v_mul_f32_e32 v150, v156, v150
	v_mul_f32_e32 v151, v157, v151
	v_fma_f32 v148, v154, v148, v154
	v_fma_f32 v149, v155, v149, v155
	v_fma_f32 v150, v156, v150, v156
	v_fma_f32 v151, v157, v151, v157
	v_mul_f32_e32 v148, 0xc0135761, v148
	v_mul_f32_e32 v149, 0xc0135761, v149
	v_mul_f32_e32 v150, 0xc0135761, v150
	v_mul_f32_e32 v151, 0xc0135761, v151
	v_exp_f32_e32 v148, v148
	v_exp_f32_e32 v149, v149
	v_exp_f32_e32 v150, v150
	v_exp_f32_e32 v151, v151
	v_add_f32_e32 v148, 1.0, v148
	v_add_f32_e32 v149, 1.0, v149
	v_add_f32_e32 v150, 1.0, v150
	v_add_f32_e32 v151, 1.0, v151
	v_rcp_f32_e32 v148, v148
	v_rcp_f32_e32 v149, v149
	v_rcp_f32_e32 v150, v150
	v_rcp_f32_e32 v151, v151
	v_mul_f32_e32 v148, v154, v148
	v_mul_f32_e32 v149, v155, v149
	v_mul_f32_e32 v150, v156, v150
	v_mul_f32_e32 v151, v157, v151
	v_cvt_pk_bf16_f32 v148, v148, v149
	v_cvt_pk_bf16_f32 v150, v150, v151
	global_store_short v[144:145], v148, off
	global_store_short_d16_hi v[144:145], v148, off offset:2048
	global_store_short v[146:147], v150, off
	global_store_short_d16_hi v[146:147], v150, off offset:2048
	v_lshl_add_u64 v[144:145], v[144:145], 0, s[82:83]
	v_lshl_add_u64 v[146:147], v[146:147], 0, s[82:83]
	s_waitcnt lgkmcnt(0)
	s_cbranch_scc1 .LBB0_1061
.Ls5u_top_3:
	s_waitcnt vmcnt(12)
	s_cmp_gt_u32 s23, 28
	s_cselect_b64 s[24:25], -1, 0
	s_nor_b64 s[28:29], s[0:1], s[24:25]
	s_and_saveexec_b64 s[24:25], s[28:29]
	s_cbranch_execz .Ls5u_body_3
	global_load_dwordx4 v[60:63], v[98:99], off nt
; #define LAS __attribute__((address_space(3)))
; __device__ __forceinline__ unsigned cvt_pk_bf16(float lo, float hi) { unsigned r; asm volatile("v_cvt_pk_bf16_f32 %0, %1, %2" : "=v"(r) : "v"(lo), "v"(hi)); return r; }
; template <bool PASSB>
; __device__ __forceinline__ void s5_phase(LAS unsigned char* lds, const Params& p) {
;     ...
;         for (int st = 0; st < NST; ++st) {
;             const size_t r0 = row0 + st * 16;
;             const bf16x8 au = au_q0; au_q0 = au_q1; au_q1 = au_q2;
;             if (st + 3 < NST) au_q2 = (fq < 2) ? *(const bf16x8*)(up + (size_t)(st + 3) * 16 * 16) : zero8;
; #pragma unroll
;             for (int nb = 0; nb < 8; ++nb) {
;                 const f32x4 d = __builtin_amdgcn_mfma_f32_16x16x32_bf16(au, bfm[nb], (f32x4){0.f, 0.f, 0.f, 0.f}, 0, 0, 0);
;                 *(LAS f32x4*)(BuL + (nb * 16 + fr) * 20 + fq * 4) = d;
;             }
;             LDS_WAIT();
;             f32x4 br4[4], bi4[4];
; #pragma unroll
;             for (int q = 0; q < 4; ++q) { br4[q] = *(const LAS f32x4*)(BuL + lane * 20 + q * 4); bi4[q] = *(const LAS f32x4*)(BuL + (64 + lane) * 20 + q * 4); }
; #pragma unroll
;             for (int t = 0; t < 16; ++t) {
;                 const float bur = br4[t >> 2][t & 3], bui = bi4[t >> 2][t & 3];
;                 const float nr = are * hr - aim * hi + bur, ni = are * hi + aim * hr + bui; hr = nr; hi = ni;
;                 if (PASSB) *(LAS unsigned*)(HbL + t * 272 + lane * 4) = cvt_pk_bf16(hr, hi);
;             }
;             if (PASSB) {
;                 LDS_WAIT();
;                 f32x4 y = __builtin_amdgcn_mfma_f32_16x16x32_bf16(au, dfm, (f32x4){0.f, 0.f, 0.f, 0.f}, 0, 0, 0);
; #pragma unroll
;                 for (int ks = 0; ks < 4; ++ks) {
;                     const bf16x8 a = *(const LAS bf16x8*)(HbL + fr * 272 + (ks * 32 + fq * 8) * 2);
;                     y = __builtin_amdgcn_mfma_f32_16x16x32_bf16(a, cfm[ks], y, 0, 0, 0);
;                 }
; #pragma unroll
;                 for (int j = 0; j < 4; ++j) {
;                     const float v = y[j];
;                     const float ge = v * sigmoidf_(1.5957691216057308f * (v + 0.044715f * v * v * v));
;                     YG[(r0 + fq * 4 + j) * 1024 + g * 16 + fr] = (bf16_t)(cvt_pk_bf16(ge, ge) & 0xffffu);
;                 }
;             }
;             LDS_WAIT();
;         }
.Ls5u_body_3:
	s_or_b64 exec, exec, s[24:25]
	v_mfma_f32_16x16x32_bf16 v[112:115], v[64:67], v[8:11], 0
	v_mfma_f32_16x16x32_bf16 v[116:119], v[64:67], v[4:7], 0
	s_nop 6
	ds_write_b128 v107, v[112:115]
	s_add_i32 s23, s23, 1
	v_mfma_f32_16x16x32_bf16 v[120:123], v[64:67], v[16:19], 0
	v_lshl_add_u64 v[98:99], v[98:99], 0, s[64:65]
	s_cmp_eq_u32 s23, 32
	v_mfma_f32_16x16x32_bf16 v[124:127], v[64:67], v[12:15], 0
	ds_write_b128 v107, v[116:119] offset:1280
	s_nop 3
	ds_write_b128 v107, v[120:123] offset:2560
	s_nop 1
	ds_write_b128 v107, v[124:127] offset:3840
	v_mfma_f32_16x16x32_bf16 v[128:131], v[64:67], v[20:23], 0
	v_mfma_f32_16x16x32_bf16 v[112:115], v[64:67], v[24:27], 0
	v_mfma_f32_16x16x32_bf16 v[116:119], v[64:67], v[28:31], 0
	s_nop 5
	ds_write_b128 v107, v[128:131] offset:5120
	ds_write_b128 v107, v[112:115] offset:6400
	ds_write_b128 v107, v[116:119] offset:7680
	v_mfma_f32_16x16x32_bf16 v[112:115], v[64:67], v[32:35], 0
	v_mfma_f32_16x16x32_bf16 v[154:157], v[64:67], v[52:55], 0
	s_nop 6
	ds_write_b128 v107, v[112:115] offset:8960
	s_waitcnt lgkmcnt(0)
	ds_read_b128 v[112:115], v108
	ds_read_b128 v[116:119], v108 offset:16
	ds_read_b128 v[120:123], v108 offset:32
	ds_read_b128 v[124:127], v108 offset:48
	ds_read_b128 v[128:131], v108 offset:5120
	ds_read_b128 v[132:135], v108 offset:5136
	ds_read_b128 v[136:139], v108 offset:5152
	ds_read_b128 v[140:143], v108 offset:5168
	s_waitcnt lgkmcnt(3)
	v_fmac_f32_e32 v112, v88, v94
	v_fmac_f32_e32 v128, v88, v95
	v_fma_f32 v112, -v92, v95, v112
	v_fmac_f32_e32 v128, v92, v94
	v_cvt_pk_bf16_f32 v1, v112, v128
	v_fmac_f32_e32 v113, v88, v112
	v_fmac_f32_e32 v129, v88, v128
	v_fma_f32 v113, -v92, v128, v113
	v_fmac_f32_e32 v129, v92, v112
	v_cvt_pk_bf16_f32 v152, v113, v129
	ds_write2_b32 v158, v1, v152 offset0:0 offset1:68
	v_fmac_f32_e32 v114, v88, v113
	v_fmac_f32_e32 v130, v88, v129
	v_fma_f32 v114, -v92, v129, v114
	v_fmac_f32_e32 v130, v92, v113
	v_cvt_pk_bf16_f32 v1, v114, v130
	v_fmac_f32_e32 v115, v88, v114
	v_fmac_f32_e32 v131, v88, v130
	v_fma_f32 v115, -v92, v130, v115
	v_fmac_f32_e32 v131, v92, v114
	v_cvt_pk_bf16_f32 v152, v115, v131
	ds_write2_b32 v158, v1, v152 offset0:136 offset1:204
	s_waitcnt lgkmcnt(4)
	v_fmac_f32_e32 v116, v88, v115
	v_fmac_f32_e32 v132, v88, v131
	v_fma_f32 v116, -v92, v131, v116
	v_fmac_f32_e32 v132, v92, v115
	v_cvt_pk_bf16_f32 v1, v116, v132
	v_fmac_f32_e32 v117, v88, v116
	v_fmac_f32_e32 v133, v88, v132
	v_fma_f32 v117, -v92, v132, v117
	v_fmac_f32_e32 v133, v92, v116
	v_cvt_pk_bf16_f32 v152, v117, v133
	ds_write2_b32 v159, v1, v152 offset0:0 offset1:68
	v_fmac_f32_e32 v118, v88, v117
	v_fmac_f32_e32 v134, v88, v133
	v_fma_f32 v118, -v92, v133, v118
	v_fmac_f32_e32 v134, v92, v117
	v_cvt_pk_bf16_f32 v1, v118, v134
	v_fmac_f32_e32 v119, v88, v118
	v_fmac_f32_e32 v135, v88, v134
	v_fma_f32 v119, -v92, v134, v119
	v_fmac_f32_e32 v135, v92, v118
	v_cvt_pk_bf16_f32 v152, v119, v135
	ds_write2_b32 v159, v1, v152 offset0:136 offset1:204
	s_waitcnt lgkmcnt(5)
	v_fmac_f32_e32 v120, v88, v119
	v_fmac_f32_e32 v136, v88, v135
	v_fma_f32 v120, -v92, v135, v120
	v_fmac_f32_e32 v136, v92, v119
	v_cvt_pk_bf16_f32 v1, v120, v136
	v_fmac_f32_e32 v121, v88, v120
	v_fmac_f32_e32 v137, v88, v136
	v_fma_f32 v121, -v92, v136, v121
	v_fmac_f32_e32 v137, v92, v120
	v_cvt_pk_bf16_f32 v152, v121, v137
	ds_write2_b32 v160, v1, v152 offset0:0 offset1:68
	v_fmac_f32_e32 v122, v88, v121
	v_fmac_f32_e32 v138, v88, v137
	v_fma_f32 v122, -v92, v137, v122
	v_fmac_f32_e32 v138, v92, v121
	v_cvt_pk_bf16_f32 v1, v122, v138
	v_fmac_f32_e32 v123, v88, v122
	v_fmac_f32_e32 v139, v88, v138
	v_fma_f32 v123, -v92, v138, v123
	v_fmac_f32_e32 v139, v92, v122
	v_cvt_pk_bf16_f32 v152, v123, v139
	ds_write2_b32 v160, v1, v152 offset0:136 offset1:204
	s_waitcnt lgkmcnt(6)
	v_fmac_f32_e32 v124, v88, v123
	v_fmac_f32_e32 v140, v88, v139
	v_fma_f32 v124, -v92, v139, v124
	v_fmac_f32_e32 v140, v92, v123
	v_cvt_pk_bf16_f32 v1, v124, v140
	v_fmac_f32_e32 v125, v88, v124
	v_fmac_f32_e32 v141, v88, v140
	v_fma_f32 v125, -v92, v140, v125
	v_fmac_f32_e32 v141, v92, v124
	v_cvt_pk_bf16_f32 v152, v125, v141
	ds_write2_b32 v161, v1, v152 offset0:0 offset1:68
	v_fmac_f32_e32 v126, v88, v125
	v_fmac_f32_e32 v142, v88, v141
	v_fma_f32 v126, -v92, v141, v126
	v_fmac_f32_e32 v142, v92, v125
	v_cvt_pk_bf16_f32 v1, v126, v142
	v_fmac_f32_e32 v127, v88, v126
	v_fmac_f32_e32 v143, v88, v142
	v_fma_f32 v127, -v92, v142, v127
	v_fmac_f32_e32 v143, v92, v126
	v_cvt_pk_bf16_f32 v152, v127, v143
	ds_write2_b32 v161, v1, v152 offset0:136 offset1:204
	v_mov_b32_e32 v94, v127
	v_mov_b32_e32 v95, v143
	s_waitcnt lgkmcnt(0)
	ds_read_b128 v[112:115], v110 offset:10240
	ds_read_b128 v[116:119], v110 offset:10304
	s_waitcnt lgkmcnt(1)
	v_mfma_f32_16x16x32_bf16 v[154:157], v[112:115], v[36:39], v[154:157]
	ds_read_b128 v[112:115], v110 offset:10368
	s_waitcnt lgkmcnt(1)
	v_mfma_f32_16x16x32_bf16 v[154:157], v[116:119], v[40:43], v[154:157]
	ds_read_b128 v[116:119], v110 offset:10432
	s_waitcnt lgkmcnt(1)
	v_mfma_f32_16x16x32_bf16 v[154:157], v[112:115], v[44:47], v[154:157]
	s_waitcnt lgkmcnt(0)
	v_mfma_f32_16x16x32_bf16 v[154:157], v[116:119], v[48:51], v[154:157]
	s_nop 7
	v_mul_f32_e32 v148, 0x3d372713, v154
	v_mul_f32_e32 v149, 0x3d372713, v155
	v_mul_f32_e32 v150, 0x3d372713, v156
	v_mul_f32_e32 v151, 0x3d372713, v157
	v_mul_f32_e32 v148, v154, v148
	v_mul_f32_e32 v149, v155, v149
	v_mul_f32_e32 v150, v156, v150
	v_mul_f32_e32 v151, v157, v151
	v_fma_f32 v148, v154, v148, v154
	v_fma_f32 v149, v155, v149, v155
	v_fma_f32 v150, v156, v150, v156
	v_fma_f32 v151, v157, v151, v157
	v_mul_f32_e32 v148, 0xc0135761, v148
	v_mul_f32_e32 v149, 0xc0135761, v149
	v_mul_f32_e32 v150, 0xc0135761, v150
	v_mul_f32_e32 v151, 0xc0135761, v151
	v_exp_f32_e32 v148, v148
	v_exp_f32_e32 v149, v149
	v_exp_f32_e32 v150, v150
	v_exp_f32_e32 v151, v151
	v_add_f32_e32 v148, 1.0, v148
	v_add_f32_e32 v149, 1.0, v149
	v_add_f32_e32 v150, 1.0, v150
	v_add_f32_e32 v151, 1.0, v151
	v_rcp_f32_e32 v148, v148
	v_rcp_f32_e32 v149, v149
	v_rcp_f32_e32 v150, v150
	v_rcp_f32_e32 v151, v151
	v_mul_f32_e32 v148, v154, v148
	v_mul_f32_e32 v149, v155, v149
	v_mul_f32_e32 v150, v156, v150
	v_mul_f32_e32 v151, v157, v151
	v_cvt_pk_bf16_f32 v148, v148, v149
	v_cvt_pk_bf16_f32 v150, v150, v151
	global_store_short v[144:145], v148, off
	global_store_short_d16_hi v[144:145], v148, off offset:2048
	global_store_short v[146:147], v150, off
	global_store_short_d16_hi v[146:147], v150, off offset:2048
	v_lshl_add_u64 v[144:145], v[144:145], 0, s[82:83]
	v_lshl_add_u64 v[146:147], v[146:147], 0, s[82:83]
	s_waitcnt lgkmcnt(0)
	s_cbranch_scc1 .LBB0_1061
	s_branch .Ls5u_top_0
